# v6 + first two waits of a tile after an epilogue count the 16 stores in (vmcnt 24), so two MFMA phases run while the stores drain
# baseline (speedup 1.0000x reference)
; #define PG8_STAGE(bufoff, gbase, voff) do { _Pragma("unroll") for (int _i = 0; _i < 2; ++_i) \
;         __builtin_amdgcn_global_load_lds((const unsigned*)((const char*)(gbase) + (voff)[_i]), (LAS unsigned*)(lds + (bufoff) + ldsw + _i * 8192), 16, 0, 0); } while (0)
; #define PG8_WAIT_V(n) asm volatile("s_waitcnt vmcnt(" #n ")" ::: "memory")
; #define PG8_BAR __builtin_amdgcn_s_barrier()
; __device__ __forceinline__ void gemm_phase(LAS unsigned char* lds, const GemmP g, const EpiP e) {
;     ...
;     const size_t ksliceB = (size_t)(g.ksplit > 1 ? g.K / g.ksplit : 0) * 2;
;     const size_t ksliceA = g.a_tiled ? (size_t)(g.ksplit > 1 ? g.K / g.ksplit / BK : 0) * 32768 : ksliceB;
;     ...
;     const char* cA = UNIT_A(cur); const char* cB = UNIT_B(cur);
;     PG8_STAGE(PG8_SB(0, 0), cB, voffB); PG8_STAGE(PG8_SB(0, 1), cB + hstepB, voffB); PG8_STAGE(PG8_SA(0, 0), cA, voffA); PG8_STAGE(PG8_SA(0, 1), cA + hstepA, voffA);
;     if (wr == 1) PG8_BAR;
;     PG8_WAIT_V(2); PG8_BAR;
;     PG8_STAGE(PG8_SB(1, 0), cB + kstepB, voffB); PG8_STAGE(PG8_SA(1, 0), cA + kstepA, voffA); PG8_STAGE(PG8_SB(1, 1), cB + hstepB + kstepB, voffB);
;     PG8_WAIT_V(6); PG8_BAR;
.LBB0_367:
	s_mov_b32 s99, 0
	v_writelane_b32 v255, s20, 22
	s_lshl_b32 s19, s64, 8
	s_lshl_b32 s7, s64, 9
	v_writelane_b32 v255, s21, 23
	v_readlane_b32 s20, v254, 30
	s_lshl_b32 s6, s20, 9
	s_and_b64 s[4:5], s[34:35], exec
	s_cselect_b32 s4, 0, 0
	s_cselect_b32 s6, s7, s6
	s_ashr_i32 s5, s87, 31
	s_mul_i32 s5, s6, s5
	s_mul_hi_u32 s7, s6, s87
	s_add_i32 s5, s7, s5
	s_mul_i32 s4, s4, s87
	s_add_i32 s5, s5, s4
	s_mul_i32 s4, s6, s87
	v_readlane_b32 s16, v255, 3
	v_readlane_b32 s17, v255, 4
	s_add_u32 s4, s16, s4
	s_addc_u32 s5, s17, s5
	s_ashr_i32 s7, s85, 31
	v_readlane_b32 s22, v255, 7
	v_readlane_b32 s23, v255, 8
	s_mul_hi_u32 s16, s22, s85
	s_mul_i32 s17, s22, s7
	s_add_i32 s16, s16, s17
	s_mul_i32 s17, s23, s85
	v_readlane_b32 s21, v254, 31
	s_add_i32 s16, s16, s17
	s_mul_i32 s17, s22, s85
	s_add_u32 s4, s4, s17
	s_mov_b32 s21, s36
	s_addc_u32 s5, s5, s16
	s_lshl_b64 s[46:47], s[20:21], 9
	s_add_u32 s78, s4, s14
	s_addc_u32 s79, s5, s15
	s_mul_i32 s4, s46, s7
	s_mul_hi_u32 s5, s46, s85
	s_add_i32 s4, s5, s4
	s_lshr_b32 s5, s20, 23
	s_mul_i32 s5, s5, s85
	s_add_i32 s4, s4, s5
	s_mul_i32 s5, s46, s85
	v_readlane_b32 s16, v254, 61
	v_readlane_b32 s17, v254, 62
	s_add_u32 s15, s16, s5
	s_addc_u32 s4, s17, s4
	s_ashr_i32 s14, s18, 6
	s_ashr_i32 s5, s18, 8
	s_and_b64 s[16:17], s[34:35], exec
	s_cselect_b32 s7, 0, 0
	s_cselect_b32 s90, s19, 0x4000
	s_lshl_b64 s[48:49], s[20:21], 8
	s_lshl_b32 s91, s14, 10
	s_add_u32 s40, s15, s12
	v_mul_lo_u32 v0, v0, s20
	s_addc_u32 s41, s4, s13
	s_add_i32 s92, s91, 0
	v_add_lshl_u32 v146, v0, v1, 1
	s_add_i32 m0, s92, 0x10000
	v_mul_lo_u32 v2, v2, s20
	global_load_lds_dwordx4 v146, s[40:41]
	s_add_i32 m0, s92, 0x12000
	v_add_lshl_u32 v144, v2, v3, 1
	s_add_u32 s12, s40, s48
	global_load_lds_dwordx4 v144, s[40:41]
	s_addc_u32 s13, s41, s49
	s_add_i32 m0, s92, 0x14000
	v_mov_b32_e32 v147, v97
	v_mov_b32_e32 v145, v97
	global_load_lds_dwordx4 v146, s[12:13]
	s_add_i32 m0, s92, 0x16000
	s_add_i32 s93, s92, 0x2000
	v_lshl_add_u64 v[4:5], s[12:13], 0, v[146:147]
	v_lshl_add_u64 v[6:7], s[12:13], 0, v[144:145]
	global_load_lds_dwordx4 v144, s[12:13]
	s_mov_b32 m0, s92
	s_add_u32 s12, s78, s90
	global_load_lds_dwordx4 v140, s[78:79]
	s_mov_b32 m0, s93
	s_addc_u32 s13, s79, s7
	s_add_i32 s73, s92, 0x4000
	global_load_lds_dwordx4 v142, s[78:79]
	s_mov_b32 m0, s73
	s_add_i32 s4, s92, 0x6000
	global_load_lds_dwordx4 v140, s[12:13]
	s_mov_b32 m0, s4
	s_cmp_eq_u32 s5, 1
	global_load_lds_dwordx4 v142, s[12:13]
	s_mov_b32 s16, s20
	s_cselect_b64 s[12:13], -1, 0
	v_writelane_b32 v254, s16, 30
	v_writelane_b32 v255, s12, 1
	v_lshl_add_u64 v[0:1], s[40:41], 0, v[146:147]
	v_writelane_b32 v254, s17, 31
	v_lshl_add_u64 v[2:3], s[40:41], 0, v[144:145]
	v_writelane_b32 v255, s13, 2
	s_cmp_lg_u32 s5, 1
	s_cbranch_scc1 .LBB0_369
	s_barrier

; #define PG8_STAGE(bufoff, gbase, voff) do { _Pragma("unroll") for (int _i = 0; _i < 2; ++_i) \
;         __builtin_amdgcn_global_load_lds((const unsigned*)((const char*)(gbase) + (voff)[_i]), (LAS unsigned*)(lds + (bufoff) + ldsw + _i * 8192), 16, 0, 0); } while (0)
; #define PG8_LDA(dst, b, h) do { _Pragma("unroll") for (int m = 0; m < 4; ++m) _Pragma("unroll") for (int k = 0; k < 2; ++k) dst[m][k] = *(const LAS bf16x8*)(lds + PG8_SA(b, h) + aoff + m * 2048 + k * 1024); } while (0)
; #define PG8_LDB(dst, b, h) do { _Pragma("unroll") for (int n = 0; n < 2; ++n) _Pragma("unroll") for (int k = 0; k < 2; ++k) dst[n][k] = *(const LAS bf16x8*)(lds + PG8_SB(b, h) + boff + n * 2048 + k * 1024); } while (0)
; #define PG8_MMA(ai, bj, At, Bt) do { __builtin_amdgcn_s_setprio(1); _Pragma("unroll") for (int m = 0; m < 4; ++m) _Pragma("unroll") for (int n = 0; n < 2; ++n) _Pragma("unroll") for (int k = 0; k < 2; ++k) \
;         acc[ai][bj][m][n] = __builtin_amdgcn_mfma_f32_16x16x32_bf16(Bt[n][k], At[m][k], acc[ai][bj][m][n], 0, 0, 0); __builtin_amdgcn_s_setprio(0); } while (0)
; #define PG8_WAIT_V(n) asm volatile("s_waitcnt vmcnt(" #n ")" ::: "memory")
; #define PG8_WAIT_L(n) asm volatile("s_waitcnt lgkmcnt(" #n ")" ::: "memory")
; #define PG8_BAR __builtin_amdgcn_s_barrier()
; #define PG8_SCHED __builtin_amdgcn_sched_barrier(0)
; __device__ __forceinline__ void gemm_phase(LAS unsigned char* lds, const GemmP g, const EpiP e) {
;     ...
;         for (int t = 0; t < nt; t += 2) {
;             const bool last = (t == nt - 2);
;             const char* a1 = cA + (size_t)(t + 1) * kstepA;
;             const char* a2 = last ? nA : cA + (size_t)(t + 2) * kstepA; const char* b2 = last ? nB : cB + (size_t)(t + 2) * kstepB;
;             const char* a3 = a2 + kstepA; const char* b3 = b2 + kstepB;
;             PG8_LDB(B0, 0, 0); PG8_LDB(B1, 0, 1); PG8_SCHED; PG8_LDA(At, 0, 0); PG8_STAGE(PG8_SA(1, 1), a1 + hstepA, voffA);
;             PG8_WAIT_V(8); PG8_WAIT_L(0); PG8_BAR; PG8_MMA(0, 0, At, B0); PG8_MMA(0, 1, At, B1); PG8_BAR; PG8_SCHED;
.LBB0_394:
	s_add_u32 s30, s18, 1
	s_addc_u32 s31, s19, 0
	s_add_u32 s16, s18, 2
	s_addc_u32 s17, s19, 0
	s_lshl_b64 s[20:21], s[16:17], s77
	s_add_u32 s19, s78, s20
	s_addc_u32 s20, s79, s21
	s_cmp_eq_u32 s26, s18
	s_cselect_b32 s21, s51, s20
	s_cselect_b32 s20, s50, s19
	s_cselect_b32 s22, s80, s27
	s_cselect_b32 s23, s81, s28
	s_add_u32 s18, s20, s38
	s_addc_u32 s19, s21, s39
	s_add_i32 s29, 0, 0x10000
	v_add_u32_e32 v96, s29, v179
	s_add_i32 s34, 0, 0x14000
	ds_read_b128 v[132:135], v96
	ds_read_b128 v[136:139], v96 offset:1024
	ds_read_b128 v[160:163], v96 offset:2048
	ds_read_b128 v[164:167], v96 offset:3072
	v_add_u32_e32 v96, s34, v179
	ds_read_b128 v[168:171], v96
	ds_read_b128 v[172:175], v96 offset:1024
	ds_read_b128 v[216:219], v96 offset:2048
	ds_read_b128 v[220:223], v96 offset:3072
	s_lshl_b64 s[30:31], s[30:31], s77
	s_add_u32 s30, s24, s30
	s_addc_u32 s31, s25, s31
	v_lshl_add_u64 v[98:99], s[30:31], 0, v[140:141]
	s_add_i32 m0, s92, 0xc000
	ds_read_b128 v[224:227], v188
	ds_read_b128 v[228:231], v188 offset:1024
	ds_read_b128 v[232:235], v188 offset:2048
	ds_read_b128 v[236:239], v188 offset:3072
	ds_read_b128 v[240:243], v188 offset:4096
	ds_read_b128 v[244:247], v188 offset:5120
	ds_read_b128 v[248:251], v188 offset:6144
	ds_read_b128 v[204:207], v188 offset:7168
	global_load_lds_dwordx4 v[98:99], off
	v_lshl_add_u64 v[98:99], s[30:31], 0, v[142:143]
	s_add_i32 m0, s92, 0xe000
	s_nop 0
	global_load_lds_dwordx4 v[98:99], off
	s_cmp_eq_u32 s99, 0
	s_cbranch_scc1 .Lrlx_n0
	s_waitcnt vmcnt(24)
	s_branch .Lrlx_j0

; #define PG8_STAGE(bufoff, gbase, voff) do { _Pragma("unroll") for (int _i = 0; _i < 2; ++_i) \
;         __builtin_amdgcn_global_load_lds((const unsigned*)((const char*)(gbase) + (voff)[_i]), (LAS unsigned*)(lds + (bufoff) + ldsw + _i * 8192), 16, 0, 0); } while (0)
; #define PG8_LDA(dst, b, h) do { _Pragma("unroll") for (int m = 0; m < 4; ++m) _Pragma("unroll") for (int k = 0; k < 2; ++k) dst[m][k] = *(const LAS bf16x8*)(lds + PG8_SA(b, h) + aoff + m * 2048 + k * 1024); } while (0)
; #define PG8_MMA(ai, bj, At, Bt) do { __builtin_amdgcn_s_setprio(1); _Pragma("unroll") for (int m = 0; m < 4; ++m) _Pragma("unroll") for (int n = 0; n < 2; ++n) _Pragma("unroll") for (int k = 0; k < 2; ++k) \
;         acc[ai][bj][m][n] = __builtin_amdgcn_mfma_f32_16x16x32_bf16(Bt[n][k], At[m][k], acc[ai][bj][m][n], 0, 0, 0); __builtin_amdgcn_s_setprio(0); } while (0)
; #define PG8_WAIT_V(n) asm volatile("s_waitcnt vmcnt(" #n ")" ::: "memory")
; #define PG8_WAIT_L(n) asm volatile("s_waitcnt lgkmcnt(" #n ")" ::: "memory")
; #define PG8_BAR __builtin_amdgcn_s_barrier()
; #define PG8_SCHED __builtin_amdgcn_sched_barrier(0)
; __device__ __forceinline__ void gemm_phase(LAS unsigned char* lds, const GemmP g, const EpiP e) {
;     ...
;             PG8_WAIT_V(8); PG8_WAIT_L(0); PG8_BAR; PG8_MMA(0, 0, At, B0); PG8_MMA(0, 1, At, B1); PG8_BAR; PG8_SCHED;
;             PG8_LDA(At, 0, 1); PG8_STAGE(PG8_SB(0, 0), b2, voffB); PG8_STAGE(PG8_SB(0, 1), b2 + hstepB, voffB); PG8_STAGE(PG8_SA(0, 0), a2, voffA);
;             PG8_WAIT_V(8); PG8_WAIT_L(0); PG8_BAR; PG8_MMA(1, 0, At, B0); PG8_MMA(1, 1, At, B1); PG8_BAR; PG8_SCHED;
.Lrlx_j0:
	s_waitcnt lgkmcnt(0)
	s_barrier
	s_setprio 1
	s_waitcnt lgkmcnt(0)
	v_mfma_f32_16x16x32_bf16 v[128:131], v[132:135], v[224:227], v[128:131]
	v_mfma_f32_16x16x32_bf16 v[124:127], v[160:163], v[224:227], v[124:127]
	v_mfma_f32_16x16x32_bf16 v[120:123], v[132:135], v[232:235], v[120:123]
	v_mfma_f32_16x16x32_bf16 v[116:119], v[160:163], v[232:235], v[116:119]
	v_mfma_f32_16x16x32_bf16 v[112:115], v[132:135], v[240:243], v[112:115]
	v_mfma_f32_16x16x32_bf16 v[108:111], v[160:163], v[240:243], v[108:111]
	v_mfma_f32_16x16x32_bf16 v[104:107], v[132:135], v[248:251], v[104:107]
	v_mfma_f32_16x16x32_bf16 v[98:101], v[160:163], v[248:251], v[100:103]
	v_mfma_f32_16x16x32_bf16 v[128:131], v[136:139], v[228:231], v[128:131]
	v_mfma_f32_16x16x32_bf16 v[124:127], v[164:167], v[228:231], v[124:127]
	v_mfma_f32_16x16x32_bf16 v[120:123], v[136:139], v[236:239], v[120:123]
	v_mfma_f32_16x16x32_bf16 v[116:119], v[164:167], v[236:239], v[116:119]
	v_mfma_f32_16x16x32_bf16 v[112:115], v[136:139], v[244:247], v[112:115]
	v_mfma_f32_16x16x32_bf16 v[108:111], v[164:167], v[244:247], v[108:111]
	v_mfma_f32_16x16x32_bf16 v[104:107], v[136:139], v[204:207], v[104:107]
	v_mfma_f32_16x16x32_bf16 v[98:101], v[164:167], v[204:207], v[98:101]
	s_setprio 0
	s_setprio 1
	v_mfma_f32_16x16x32_bf16 v[92:95], v[168:171], v[224:227], v[92:95]
	v_mfma_f32_16x16x32_bf16 v[88:91], v[216:219], v[224:227], v[88:91]
	v_mfma_f32_16x16x32_bf16 v[84:87], v[168:171], v[232:235], v[84:87]
	v_mfma_f32_16x16x32_bf16 v[80:83], v[216:219], v[232:235], v[80:83]
	v_mfma_f32_16x16x32_bf16 v[76:79], v[168:171], v[240:243], v[76:79]
	v_mfma_f32_16x16x32_bf16 v[72:75], v[216:219], v[240:243], v[72:75]
	v_mfma_f32_16x16x32_bf16 v[68:71], v[168:171], v[248:251], v[68:71]
	v_mfma_f32_16x16x32_bf16 v[64:67], v[216:219], v[248:251], v[64:67]
	v_mfma_f32_16x16x32_bf16 v[92:95], v[172:175], v[228:231], v[92:95]
	v_mfma_f32_16x16x32_bf16 v[88:91], v[220:223], v[228:231], v[88:91]
	v_mfma_f32_16x16x32_bf16 v[84:87], v[172:175], v[236:239], v[84:87]
	v_mfma_f32_16x16x32_bf16 v[80:83], v[220:223], v[236:239], v[80:83]
	v_mfma_f32_16x16x32_bf16 v[76:79], v[172:175], v[244:247], v[76:79]
	v_mfma_f32_16x16x32_bf16 v[72:75], v[220:223], v[244:247], v[72:75]
	v_mfma_f32_16x16x32_bf16 v[68:71], v[172:175], v[204:207], v[68:71]
	v_mfma_f32_16x16x32_bf16 v[64:67], v[220:223], v[204:207], v[64:67]
	s_setprio 0
	s_barrier
	s_add_i32 s29, s29, s91
	v_lshl_add_u64 v[176:177], s[22:23], 0, v[146:147]
	s_mov_b32 m0, s29
	ds_read_b128 v[204:207], v188 offset:16384
	ds_read_b128 v[224:227], v188 offset:17408
	ds_read_b128 v[228:231], v188 offset:18432
	ds_read_b128 v[232:235], v188 offset:19456
	ds_read_b128 v[236:239], v188 offset:20480
	ds_read_b128 v[240:243], v188 offset:21504
	ds_read_b128 v[244:247], v188 offset:22528
	ds_read_b128 v[248:251], v188 offset:23552
	global_load_lds_dwordx4 v[176:177], off
	s_add_i32 m0, s29, 0x2000
	v_lshl_add_u64 v[210:211], s[22:23], 0, v[144:145]
	s_add_u32 s22, s22, s48
	s_addc_u32 s23, s23, s49
	s_add_i32 s29, s34, s91
	global_load_lds_dwordx4 v[210:211], off
	v_lshl_add_u64 v[212:213], s[22:23], 0, v[146:147]
	s_mov_b32 m0, s29
	v_lshl_add_u64 v[190:191], s[22:23], 0, v[144:145]
	global_load_lds_dwordx4 v[212:213], off
	s_add_i32 m0, s29, 0x2000
	v_lshl_add_u64 v[102:103], s[20:21], 0, v[140:141]
	global_load_lds_dwordx4 v[190:191], off
	s_mov_b32 m0, s92
	s_nop 0
	global_load_lds_dwordx4 v[102:103], off
	v_lshl_add_u64 v[102:103], s[20:21], 0, v[142:143]
	s_mov_b32 m0, s93
	s_nop 0
	global_load_lds_dwordx4 v[102:103], off
	s_cmp_eq_u32 s99, 0
	s_cbranch_scc1 .Lrlx_n1
	s_waitcnt vmcnt(24)
	s_branch .Lrlx_j1

; #define PG8_STAGE(bufoff, gbase, voff) do { _Pragma("unroll") for (int _i = 0; _i < 2; ++_i) \
;         __builtin_amdgcn_global_load_lds((const unsigned*)((const char*)(gbase) + (voff)[_i]), (LAS unsigned*)(lds + (bufoff) + ldsw + _i * 8192), 16, 0, 0); } while (0)
; #define PG8_LDA(dst, b, h) do { _Pragma("unroll") for (int m = 0; m < 4; ++m) _Pragma("unroll") for (int k = 0; k < 2; ++k) dst[m][k] = *(const LAS bf16x8*)(lds + PG8_SA(b, h) + aoff + m * 2048 + k * 1024); } while (0)
; #define PG8_LDB(dst, b, h) do { _Pragma("unroll") for (int n = 0; n < 2; ++n) _Pragma("unroll") for (int k = 0; k < 2; ++k) dst[n][k] = *(const LAS bf16x8*)(lds + PG8_SB(b, h) + boff + n * 2048 + k * 1024); } while (0)
; #define PG8_MMA(ai, bj, At, Bt) do { __builtin_amdgcn_s_setprio(1); _Pragma("unroll") for (int m = 0; m < 4; ++m) _Pragma("unroll") for (int n = 0; n < 2; ++n) _Pragma("unroll") for (int k = 0; k < 2; ++k) \
;         acc[ai][bj][m][n] = __builtin_amdgcn_mfma_f32_16x16x32_bf16(Bt[n][k], At[m][k], acc[ai][bj][m][n], 0, 0, 0); __builtin_amdgcn_s_setprio(0); } while (0)
; #define PG8_WAIT_V(n) asm volatile("s_waitcnt vmcnt(" #n ")" ::: "memory")
; #define PG8_WAIT_L(n) asm volatile("s_waitcnt lgkmcnt(" #n ")" ::: "memory")
; #define PG8_BAR __builtin_amdgcn_s_barrier()
; #define PG8_SCHED __builtin_amdgcn_sched_barrier(0)
; __device__ __forceinline__ void gemm_phase(LAS unsigned char* lds, const GemmP g, const EpiP e) {
;     ...
;             PG8_WAIT_V(8); PG8_WAIT_L(0); PG8_BAR; PG8_MMA(1, 0, At, B0); PG8_MMA(1, 1, At, B1); PG8_BAR; PG8_SCHED;
;             PG8_LDB(B0, 1, 0); PG8_LDB(B1, 1, 1); PG8_SCHED; PG8_LDA(At, 1, 0); PG8_STAGE(PG8_SA(0, 1), a2 + hstepA, voffA);
;             PG8_WAIT_V(8); PG8_WAIT_L(0); PG8_BAR; PG8_MMA(0, 0, At, B0); PG8_MMA(0, 1, At, B1); PG8_BAR; PG8_SCHED;
.Lrlx_j1:
	s_waitcnt lgkmcnt(0)
	s_barrier
	s_setprio 1
	s_waitcnt lgkmcnt(0)
	v_mfma_f32_16x16x32_bf16 v[60:63], v[132:135], v[204:207], v[60:63]
	v_mfma_f32_16x16x32_bf16 v[56:59], v[160:163], v[204:207], v[56:59]
	v_mfma_f32_16x16x32_bf16 v[52:55], v[132:135], v[228:231], v[52:55]
	v_mfma_f32_16x16x32_bf16 v[48:51], v[160:163], v[228:231], v[48:51]
	v_mfma_f32_16x16x32_bf16 v[44:47], v[132:135], v[236:239], v[44:47]
	v_mfma_f32_16x16x32_bf16 v[40:43], v[160:163], v[236:239], v[40:43]
	v_mfma_f32_16x16x32_bf16 v[36:39], v[132:135], v[244:247], v[36:39]
	v_mfma_f32_16x16x32_bf16 v[32:35], v[160:163], v[244:247], v[32:35]
	v_mfma_f32_16x16x32_bf16 v[60:63], v[136:139], v[224:227], v[60:63]
	v_mfma_f32_16x16x32_bf16 v[56:59], v[164:167], v[224:227], v[56:59]
	v_mfma_f32_16x16x32_bf16 v[52:55], v[136:139], v[232:235], v[52:55]
	v_mfma_f32_16x16x32_bf16 v[48:51], v[164:167], v[232:235], v[48:51]
	v_mfma_f32_16x16x32_bf16 v[44:47], v[136:139], v[240:243], v[44:47]
	v_mfma_f32_16x16x32_bf16 v[40:43], v[164:167], v[240:243], v[40:43]
	v_mfma_f32_16x16x32_bf16 v[36:39], v[136:139], v[248:251], v[36:39]
	v_mfma_f32_16x16x32_bf16 v[32:35], v[164:167], v[248:251], v[32:35]
	s_setprio 0
	s_setprio 1
	v_mfma_f32_16x16x32_bf16 v[28:31], v[168:171], v[204:207], v[28:31]
	v_mfma_f32_16x16x32_bf16 v[24:27], v[216:219], v[204:207], v[24:27]
	v_mfma_f32_16x16x32_bf16 v[20:23], v[168:171], v[228:231], v[20:23]
	v_mfma_f32_16x16x32_bf16 v[16:19], v[216:219], v[228:231], v[16:19]
	v_mfma_f32_16x16x32_bf16 v[12:15], v[168:171], v[236:239], v[12:15]
	v_mfma_f32_16x16x32_bf16 v[8:11], v[216:219], v[236:239], v[8:11]
	v_mfma_f32_16x16x32_bf16 v[4:7], v[168:171], v[244:247], v[4:7]
	v_mfma_f32_16x16x32_bf16 v[0:3], v[216:219], v[244:247], v[0:3]
	v_mfma_f32_16x16x32_bf16 v[28:31], v[172:175], v[224:227], v[28:31]
	v_mfma_f32_16x16x32_bf16 v[24:27], v[220:223], v[224:227], v[24:27]
	v_mfma_f32_16x16x32_bf16 v[20:23], v[172:175], v[232:235], v[20:23]
	v_mfma_f32_16x16x32_bf16 v[16:19], v[220:223], v[232:235], v[16:19]
	v_mfma_f32_16x16x32_bf16 v[12:15], v[172:175], v[240:243], v[12:15]
	v_mfma_f32_16x16x32_bf16 v[8:11], v[220:223], v[240:243], v[8:11]
	v_mfma_f32_16x16x32_bf16 v[4:7], v[172:175], v[248:251], v[4:7]
	v_mfma_f32_16x16x32_bf16 v[0:3], v[220:223], v[248:251], v[0:3]
	s_setprio 0
	s_barrier
	s_add_i32 s22, 0, 0x18000
	v_add_u32_e32 v96, s22, v179
	s_add_i32 s23, 0, 0x1c000
	ds_read_b128 v[132:135], v96
	ds_read_b128 v[136:139], v96 offset:1024
	ds_read_b128 v[160:163], v96 offset:2048
	ds_read_b128 v[164:167], v96 offset:3072
	v_add_u32_e32 v96, s23, v179
	ds_read_b128 v[168:171], v96
	ds_read_b128 v[172:175], v96 offset:1024
	ds_read_b128 v[204:207], v96 offset:2048
	ds_read_b128 v[216:219], v96 offset:3072
	s_add_u32 s20, s20, s90
	s_addc_u32 s21, s21, s7
	s_mov_b32 m0, s73
	v_lshl_add_u64 v[102:103], s[20:21], 0, v[140:141]
	ds_read_b128 v[220:223], v188 offset:32768
	ds_read_b128 v[224:227], v188 offset:33792
	ds_read_b128 v[228:231], v188 offset:34816
	ds_read_b128 v[232:235], v188 offset:35840
	ds_read_b128 v[236:239], v188 offset:36864
	ds_read_b128 v[240:243], v188 offset:37888
	ds_read_b128 v[244:247], v188 offset:38912
	ds_read_b128 v[248:251], v188 offset:39936
	global_load_lds_dwordx4 v[102:103], off
	v_lshl_add_u64 v[102:103], s[20:21], 0, v[142:143]
	s_mov_b32 m0, s4
	s_nop 0
	global_load_lds_dwordx4 v[102:103], off
	s_waitcnt vmcnt(8)
	s_waitcnt lgkmcnt(0)
	s_barrier
	s_setprio 1
	s_waitcnt lgkmcnt(0)
	v_mfma_f32_16x16x32_bf16 v[128:131], v[132:135], v[220:223], v[128:131]
	v_mfma_f32_16x16x32_bf16 v[124:127], v[160:163], v[220:223], v[124:127]
	v_mfma_f32_16x16x32_bf16 v[120:123], v[132:135], v[228:231], v[120:123]
	v_mfma_f32_16x16x32_bf16 v[116:119], v[160:163], v[228:231], v[116:119]
	v_mfma_f32_16x16x32_bf16 v[112:115], v[132:135], v[236:239], v[112:115]
	v_mfma_f32_16x16x32_bf16 v[108:111], v[160:163], v[236:239], v[108:111]
	v_mfma_f32_16x16x32_bf16 v[102:105], v[132:135], v[244:247], v[104:107]
	v_mfma_f32_16x16x32_bf16 v[98:101], v[160:163], v[244:247], v[98:101]
	v_mfma_f32_16x16x32_bf16 v[128:131], v[136:139], v[224:227], v[128:131]
	v_mfma_f32_16x16x32_bf16 v[124:127], v[164:167], v[224:227], v[124:127]
	v_mfma_f32_16x16x32_bf16 v[120:123], v[136:139], v[232:235], v[120:123]
	v_mfma_f32_16x16x32_bf16 v[116:119], v[164:167], v[232:235], v[116:119]
	v_mfma_f32_16x16x32_bf16 v[112:115], v[136:139], v[240:243], v[112:115]
	v_mfma_f32_16x16x32_bf16 v[108:111], v[164:167], v[240:243], v[108:111]
	v_mfma_f32_16x16x32_bf16 v[104:107], v[136:139], v[248:251], v[102:105]
	v_mfma_f32_16x16x32_bf16 v[100:103], v[164:167], v[248:251], v[98:101]
	s_setprio 0
	s_setprio 1
	v_mfma_f32_16x16x32_bf16 v[92:95], v[168:171], v[220:223], v[92:95]
	v_mfma_f32_16x16x32_bf16 v[88:91], v[204:207], v[220:223], v[88:91]
	v_mfma_f32_16x16x32_bf16 v[84:87], v[168:171], v[228:231], v[84:87]
	v_mfma_f32_16x16x32_bf16 v[80:83], v[204:207], v[228:231], v[80:83]
	v_mfma_f32_16x16x32_bf16 v[76:79], v[168:171], v[236:239], v[76:79]
	v_mfma_f32_16x16x32_bf16 v[72:75], v[204:207], v[236:239], v[72:75]
	v_mfma_f32_16x16x32_bf16 v[68:71], v[168:171], v[244:247], v[68:71]
	v_mfma_f32_16x16x32_bf16 v[64:67], v[204:207], v[244:247], v[64:67]
	v_mfma_f32_16x16x32_bf16 v[92:95], v[172:175], v[224:227], v[92:95]
	v_mfma_f32_16x16x32_bf16 v[88:91], v[216:219], v[224:227], v[88:91]
	v_mfma_f32_16x16x32_bf16 v[84:87], v[172:175], v[232:235], v[84:87]
	v_mfma_f32_16x16x32_bf16 v[80:83], v[216:219], v[232:235], v[80:83]
	v_mfma_f32_16x16x32_bf16 v[76:79], v[172:175], v[240:243], v[76:79]
	v_mfma_f32_16x16x32_bf16 v[72:75], v[216:219], v[240:243], v[72:75]
	v_mfma_f32_16x16x32_bf16 v[68:71], v[172:175], v[248:251], v[68:71]
	v_mfma_f32_16x16x32_bf16 v[64:67], v[216:219], v[248:251], v[64:67]
	s_setprio 0
	s_barrier
; #define PG8_STAGE(bufoff, gbase, voff) do { _Pragma("unroll") for (int _i = 0; _i < 2; ++_i) \
;         __builtin_amdgcn_global_load_lds((const unsigned*)((const char*)(gbase) + (voff)[_i]), (LAS unsigned*)(lds + (bufoff) + ldsw + _i * 8192), 16, 0, 0); } while (0)
; #define PG8_LDA(dst, b, h) do { _Pragma("unroll") for (int m = 0; m < 4; ++m) _Pragma("unroll") for (int k = 0; k < 2; ++k) dst[m][k] = *(const LAS bf16x8*)(lds + PG8_SA(b, h) + aoff + m * 2048 + k * 1024); } while (0)
; #define PG8_MMA(ai, bj, At, Bt) do { __builtin_amdgcn_s_setprio(1); _Pragma("unroll") for (int m = 0; m < 4; ++m) _Pragma("unroll") for (int n = 0; n < 2; ++n) _Pragma("unroll") for (int k = 0; k < 2; ++k) \
;         acc[ai][bj][m][n] = __builtin_amdgcn_mfma_f32_16x16x32_bf16(Bt[n][k], At[m][k], acc[ai][bj][m][n], 0, 0, 0); __builtin_amdgcn_s_setprio(0); } while (0)
; #define PG8_WAIT_V(n) asm volatile("s_waitcnt vmcnt(" #n ")" ::: "memory")
; #define PG8_WAIT_L(n) asm volatile("s_waitcnt lgkmcnt(" #n ")" ::: "memory")
; #define PG8_BAR __builtin_amdgcn_s_barrier()
; #define PG8_SCHED __builtin_amdgcn_sched_barrier(0)
; __device__ __forceinline__ void gemm_phase(LAS unsigned char* lds, const GemmP g, const EpiP e) {
;     ...
;             PG8_LDA(At, 1, 1); PG8_STAGE(PG8_SB(1, 0), b3, voffB); PG8_STAGE(PG8_SB(1, 1), b3 + hstepB, voffB); PG8_STAGE(PG8_SA(1, 0), a3, voffA);
;             PG8_WAIT_V(8); PG8_WAIT_L(0); PG8_BAR; PG8_MMA(1, 0, At, B0); PG8_MMA(1, 1, At, B1); PG8_BAR; PG8_SCHED;
;         }
	s_add_i32 s20, s22, s91
	v_lshl_add_u64 v[98:99], v[176:177], 0, s[96:97]
	s_mov_b32 m0, s20
	ds_read_b128 v[220:223], v188 offset:49152
	ds_read_b128 v[224:227], v188 offset:50176
	ds_read_b128 v[228:231], v188 offset:51200
	ds_read_b128 v[232:235], v188 offset:52224
	ds_read_b128 v[236:239], v188 offset:53248
	ds_read_b128 v[240:243], v188 offset:54272
	ds_read_b128 v[244:247], v188 offset:55296
	ds_read_b128 v[248:251], v188 offset:56320
	global_load_lds_dwordx4 v[98:99], off
	v_lshl_add_u64 v[98:99], v[210:211], 0, s[96:97]
	s_add_i32 m0, s20, 0x2000
	s_add_i32 s20, s23, s91
	global_load_lds_dwordx4 v[98:99], off
	v_lshl_add_u64 v[98:99], v[212:213], 0, s[96:97]
	s_mov_b32 m0, s20
	s_nop 0
	global_load_lds_dwordx4 v[98:99], off
	v_lshl_add_u64 v[98:99], v[190:191], 0, s[96:97]
	s_add_i32 m0, s20, 0x2000
	s_nop 0
	global_load_lds_dwordx4 v[98:99], off
	v_lshl_add_u64 v[98:99], s[18:19], 0, v[140:141]
	s_mov_b32 m0, s5
	s_nop 0
	global_load_lds_dwordx4 v[98:99], off
	v_lshl_add_u64 v[98:99], s[18:19], 0, v[142:143]
	s_mov_b32 m0, s44
	s_nop 0
	global_load_lds_dwordx4 v[98:99], off
	s_waitcnt vmcnt(8)
	s_waitcnt lgkmcnt(0)
	s_barrier
	s_setprio 1
	s_waitcnt lgkmcnt(0)
	v_mfma_f32_16x16x32_bf16 v[60:63], v[132:135], v[220:223], v[60:63]
	v_mfma_f32_16x16x32_bf16 v[56:59], v[160:163], v[220:223], v[56:59]
	v_mfma_f32_16x16x32_bf16 v[52:55], v[132:135], v[228:231], v[52:55]
	v_mfma_f32_16x16x32_bf16 v[48:51], v[160:163], v[228:231], v[48:51]
	v_mfma_f32_16x16x32_bf16 v[44:47], v[132:135], v[236:239], v[44:47]
	v_mfma_f32_16x16x32_bf16 v[40:43], v[160:163], v[236:239], v[40:43]
	v_mfma_f32_16x16x32_bf16 v[36:39], v[132:135], v[244:247], v[36:39]
	v_mfma_f32_16x16x32_bf16 v[32:35], v[160:163], v[244:247], v[32:35]
	v_mfma_f32_16x16x32_bf16 v[60:63], v[136:139], v[224:227], v[60:63]
	v_mfma_f32_16x16x32_bf16 v[56:59], v[164:167], v[224:227], v[56:59]
	v_mfma_f32_16x16x32_bf16 v[52:55], v[136:139], v[232:235], v[52:55]
	v_mfma_f32_16x16x32_bf16 v[48:51], v[164:167], v[232:235], v[48:51]
	v_mfma_f32_16x16x32_bf16 v[44:47], v[136:139], v[240:243], v[44:47]
	v_mfma_f32_16x16x32_bf16 v[40:43], v[164:167], v[240:243], v[40:43]
	v_mfma_f32_16x16x32_bf16 v[36:39], v[136:139], v[248:251], v[36:39]
	v_mfma_f32_16x16x32_bf16 v[32:35], v[164:167], v[248:251], v[32:35]
	s_setprio 0
	s_setprio 1
	v_mfma_f32_16x16x32_bf16 v[28:31], v[168:171], v[220:223], v[28:31]
	v_mfma_f32_16x16x32_bf16 v[24:27], v[204:207], v[220:223], v[24:27]
	v_mfma_f32_16x16x32_bf16 v[20:23], v[168:171], v[228:231], v[20:23]
	v_mfma_f32_16x16x32_bf16 v[16:19], v[204:207], v[228:231], v[16:19]
	v_mfma_f32_16x16x32_bf16 v[12:15], v[168:171], v[236:239], v[12:15]
	v_mfma_f32_16x16x32_bf16 v[8:11], v[204:207], v[236:239], v[8:11]
	v_mfma_f32_16x16x32_bf16 v[4:7], v[168:171], v[244:247], v[4:7]
	v_mfma_f32_16x16x32_bf16 v[0:3], v[204:207], v[244:247], v[0:3]
	v_mfma_f32_16x16x32_bf16 v[28:31], v[172:175], v[224:227], v[28:31]
	v_mfma_f32_16x16x32_bf16 v[24:27], v[216:219], v[224:227], v[24:27]
	v_mfma_f32_16x16x32_bf16 v[20:23], v[172:175], v[232:235], v[20:23]
	v_mfma_f32_16x16x32_bf16 v[16:19], v[216:219], v[232:235], v[16:19]
	v_mfma_f32_16x16x32_bf16 v[12:15], v[172:175], v[240:243], v[12:15]
	v_mfma_f32_16x16x32_bf16 v[8:11], v[216:219], v[240:243], v[8:11]
	v_mfma_f32_16x16x32_bf16 v[4:7], v[172:175], v[248:251], v[4:7]
	v_mfma_f32_16x16x32_bf16 v[0:3], v[216:219], v[248:251], v[0:3]
	s_setprio 0
	s_barrier
	s_add_u32 s27, s27, 0x100
	s_addc_u32 s28, s28, 0
	s_mov_b32 s99, 0
	s_cmp_ge_i32 s16, s69
	s_mov_b64 s[18:19], s[16:17]
	s_cbranch_scc0 .LBB0_394

; __device__ __forceinline__ void gemm_phase(LAS unsigned char* lds, const GemmP g, const EpiP e) {
;     ...
;         epi_store(acc, cur, wr, wc, fr, fq, e);
.Lrp_end1:
	s_mov_b32 s99, 1

; __device__ __forceinline__ void gemm_phase(LAS unsigned char* lds, const GemmP g, const EpiP e) {
;     ...
;         epi_store(acc, cur, wr, wc, fr, fq, e);
;         if (!has_next) break;
.Lep_done:
	s_mov_b32 s99, 1
	s_and_b64 vcc, exec, s[14:15]
	s_cbranch_vccnz .LBB0_371
